# two s_nop pads after the MLA prio block (code phase +20 bytes vs baseline)
# speedup vs baseline: 1.0087x; 1.0055x over previous
; #define DMA_K(t, slot) do { const bf16_t* s_ = Knp + (long)(t) * (KVBLK * LDK); const unsigned d_ = (unsigned)__builtin_amdgcn_readfirstlane(kn_dst + (slot) * SHM_KN); \
;     glds16s(s_, kn_off, d_); glds16s(s_ + 16 * LDK, kn_off, d_ + 4096); glds16s(Krp + (long)(t) * (KVBLK * 64), kr_off, (unsigned)__builtin_amdgcn_readfirstlane(kr_dst + (slot) * SHM_KR)); } while (0)
; #define DMA_V(t, slot) do { const bf16_t* s_ = Vp + (long)(t) * (KVBLK * LDK); const unsigned d_ = (unsigned)__builtin_amdgcn_readfirstlane(v_dst + (slot) * SHM_V); \
;     glds16s(s_, v_off, d_); glds16s(s_ + 32 * LDK, v_off, d_ + 8192); } while (0)
; __device__ __forceinline__ void mla_unit(char* lds, const bf16_t* __restrict__ Qp, const bf16_t* __restrict__ Knp, const bf16_t* __restrict__ Vp, ...
;     ...
;   const int pk = (wid & 3) + 8 * (wid >> 2);
;   const int krow_n = 4 * pk + (lane >> 4);
;   const unsigned kn_off = (unsigned)(krow_n * LDK + (((lane & 15) ^ (krow_n & 15)) << 3)) * 2u;
;   const int krow_r = 8 * wid + (lane >> 3);
;   const unsigned kr_off = (unsigned)(krow_r * 64 + (((lane & 7) ^ ((krow_r >> 1) & 7)) << 3)) * 2u;
;   const int vst_ = 2 * wid + (lane >> 5), vkk = (vst_ >> 2) * 8 + ((lane >> 2) & 7), vkey = (vkk & ~0xC) | ((vkk & 4) << 1) | ((vkk & 8) >> 1), vcol = (vst_ & 3) * 32 + (lane & 3) * 8;
;   const unsigned v_off = (unsigned)(vkey * LDK + vcol) * 2u;
;   const unsigned kn_dst = lds0 + P_KN + pk * 1024, kr_dst = lds0 + P_KR + wid * 1024, v_dst = lds0 + P_V + wid * 1024;
;     ...
;   if (first) { DMA_K(0, 0); DMA_V(0, 0); DMA_K(1, 1); DMA_V(1, 1); DMA_K(2, 2); }
.Lmla_prio_skip:
	s_nop 0
	s_nop 0
	s_ashr_i32 s5, s0, 5
	s_and_b32 s1, s8, 3
	s_and_b32 s5, s5, -8
	s_or_b32 s1, s1, s5
	s_lshl_b32 s5, s1, 2
	s_ashr_i32 s12, s0, 4
	v_bfe_u32 v1, v50, 4, 2
	s_ashr_i32 s7, s6, 31
	s_and_b32 s13, s12, 0x7ffff0
	s_lshr_b32 s12, s12, 1
	v_or_b32_e32 v2, s5, v1
	v_bitop3_b32 v1, s5, v50, v1 bitop3:0x36
	s_bfe_u32 s38, s74, 0x40005
	s_lshl_b64 s[30:31], s[6:7], 22
	s_lshl_b64 s[36:37], s[6:7], 20
	s_lshl_b32 s9, s8, 1
	s_and_b32 s12, s12, 4
	s_lshl_b32 s72, s1, 10
	v_lshlrev_b32_e32 v2, 9, v2
	v_lshlrev_b32_e32 v1, 4, v1
	s_cmp_lg_u32 0, -1
	v_and_or_b32 v197, v1, s53, v2
	v_bfe_u32 v1, v50, 3, 3
	s_cselect_b32 s1, 0, 0
	s_lshl_b32 s71, s8, 10
	v_lshl_or_b32 v1, s8, 3, v1
	s_add_i32 s14, s1, s72
	s_add_i32 s73, s71, s1
	v_lshlrev_b32_e32 v2, 7, v1
	v_lshrrev_b32_e32 v1, 1, v1
	s_add_i32 s76, s14, 0xc000
	s_add_i32 s75, s73, 0x18000
	v_readlane_b32 s1, v253, 3
	v_xor_b32_e32 v1, v1, v50
	s_cmp_lg_u32 s74, s1
	v_lshlrev_b32_e32 v1, 4, v1
	s_movk_i32 s1, 0x70
	v_and_or_b32 v198, v1, s1, v2
	v_lshrrev_b32_e32 v1, 2, v50
	v_lshrrev_b32_e32 v2, 1, v50
	v_bfe_u32 v49, v50, 5, 1
	v_and_or_b32 v1, v1, 3, s13
	v_and_b32_e32 v2, 8, v2
	v_lshlrev_b32_e32 v48, 4, v50
	v_or3_b32 v1, v1, v2, s12
	v_and_or_b32 v2, s9, 2, v49
	v_and_b32_e32 v3, 48, v48
	v_lshl_or_b32 v2, v2, 6, v3
	v_lshl_or_b32 v199, v1, 9, v2
	s_cbranch_scc1 .LBB0_238
	s_lshl_b32 s1, s38, 23
	v_readlane_b32 s5, v254, 62
	s_add_u32 s1, s5, s1
	v_readlane_b32 s5, v254, 63
	s_addc_u32 s5, s5, 0
	s_add_u32 s12, s1, s30
	s_addc_u32 s13, s5, s31
	s_add_u32 s14, s12, 0x100
	s_addc_u32 s15, s13, 0
	s_add_u32 s16, s26, s36
	s_addc_u32 s17, s27, s37
	s_mov_b32 s1, m0
	s_mov_b32 m0, s76
	s_nop 0
	global_load_lds_dwordx4 v197, s[12:13]
	s_mov_b32 m0, s1
	s_add_u32 s18, s12, 0x2000
	s_addc_u32 s19, s13, 0
	s_add_i32 s1, s76, 0x1000
	s_mov_b32 s5, m0
	s_mov_b32 m0, s1
	s_nop 0
	global_load_lds_dwordx4 v197, s[18:19]
	s_mov_b32 m0, s5
	s_mov_b32 s1, m0
	s_mov_b32 m0, s75
	s_nop 0
	global_load_lds_dwordx4 v198, s[16:17]
	s_mov_b32 m0, s1
	s_nop 0
	s_mov_b32 s1, m0
	s_mov_b32 m0, s73
	s_nop 0
	global_load_lds_dwordx4 v199, s[14:15]
	s_mov_b32 m0, s1
	s_add_u32 s14, s12, 0x4100
	s_addc_u32 s15, s13, 0
	s_add_i32 s1, s73, 0x2000
	s_mov_b32 s5, m0
	s_mov_b32 m0, s1
	s_nop 0
	global_load_lds_dwordx4 v199, s[14:15]
	s_mov_b32 m0, s5
	s_add_u32 s14, s12, 0x8000
	s_addc_u32 s15, s13, 0
	s_cmp_lg_u32 0, -1
	s_cselect_b32 s1, 0, 0
	s_add_i32 s5, s1, s72
	s_add_i32 s9, s5, 0x10000
	s_mov_b32 s18, m0
	s_mov_b32 m0, s9
	s_nop 0
	global_load_lds_dwordx4 v197, s[14:15]
	s_mov_b32 m0, s18
	s_add_u32 s14, s12, 0xa000
	s_addc_u32 s15, s13, 0
	s_add_i32 s9, s5, 0x11000
	s_mov_b32 s18, m0
	s_mov_b32 m0, s9
	s_nop 0
	global_load_lds_dwordx4 v197, s[14:15]
	s_mov_b32 m0, s18
	s_add_u32 s14, s16, 0x2000
	s_addc_u32 s15, s17, 0
	s_add_i32 s1, s1, s71
	s_add_i32 s9, s1, 0x1a000
	s_mov_b32 s18, m0
	s_mov_b32 m0, s9
	s_nop 0
	global_load_lds_dwordx4 v198, s[14:15]
	s_mov_b32 m0, s18
	s_add_u32 s14, s12, 0x8100
	s_addc_u32 s15, s13, 0
	s_add_i32 s9, s1, 0x4000
	s_mov_b32 s18, m0
	s_mov_b32 m0, s9
	s_nop 0
	global_load_lds_dwordx4 v199, s[14:15]
	s_mov_b32 m0, s18
	s_add_u32 s14, s12, 0xc100
	s_addc_u32 s15, s13, 0
	s_add_i32 s9, s1, 0x6000
	s_mov_b32 s18, m0
	s_mov_b32 m0, s9
	s_nop 0
	global_load_lds_dwordx4 v199, s[14:15]
	s_mov_b32 m0, s18
	s_add_u32 s14, s12, 0x10000
	s_addc_u32 s15, s13, 0
	s_add_i32 s9, s5, 0x14000
	s_add_u32 s12, s12, 0x12000
	s_mov_b32 s18, m0
	s_mov_b32 m0, s9
	s_nop 0
	global_load_lds_dwordx4 v197, s[14:15]
	s_mov_b32 m0, s18
	s_addc_u32 s13, s13, 0
	s_add_i32 s5, s5, 0x15000
	s_mov_b32 s9, m0
	s_mov_b32 m0, s5
	s_nop 0
	global_load_lds_dwordx4 v197, s[12:13]
	s_mov_b32 m0, s9
	s_add_u32 s12, s16, 0x4000
	s_addc_u32 s13, s17, 0
	s_add_i32 s1, s1, 0x1c000
	s_mov_b32 s5, m0
	s_mov_b32 m0, s1
	s_nop 0
	global_load_lds_dwordx4 v198, s[12:13]
	s_mov_b32 m0, s5
